# hand-written EpiRg epilogue (P3 RG-LRU gate GEMM): packed f32, log1p via ln(1+e)*e/((1+e)-1), hardware sqrt, all loads up front
# speedup vs baseline: 1.0605x; 1.0096x over previous
.LBB0_810:
	v_mbcnt_lo_u32_b32 v164, -1, 0
	v_mbcnt_hi_u32_b32 v164, -1, v164
	s_lshl_b32 s23, s9, 7
	s_and_b32 s27, s33, 3
	s_lshl_b32 s27, s27, 5
	s_add_i32 s23, s23, s27
	v_and_b32_e32 v165, 15, v164
	v_lshrrev_b32_e32 v166, 4, v164
	v_lshl_add_u32 v167, v166, 3, s23
	s_lshl_b32 s23, s8, 8
	s_lshr_b32 s27, s33, 2
	s_lshl_b32 s27, s27, 6
	s_add_i32 s23, s23, s27
	v_add_u32_e32 v168, s23, v165
	v_lshlrev_b32_e32 v169, 2, v167
	v_lshlrev_b32_e32 v170, 10, v168
	v_lshl_add_u32 v170, v167, 1, v170
	v_mov_b32_e32 v56, v170
	v_add_u32_e32 v57, 0x4000, v170
	v_add_u32_e32 v58, 0x8000, v170
	v_add_u32_e32 v59, 0xc000, v170
	v_add_u32_e32 v60, 0x20000, v170
	v_add_u32_e32 v61, 0x24000, v170
	v_add_u32_e32 v62, 0x28000, v170
	v_add_u32_e32 v63, 0x2c000, v170
	global_load_dwordx4 v[180:183], v169, s[76:77]
	global_load_dwordx4 v[184:187], v169, s[76:77] offset:16
	global_load_dwordx4 v[188:191], v169, s[80:81]
	global_load_dwordx4 v[192:195], v169, s[80:81] offset:16
	global_load_dwordx4 v[196:199], v169, s[82:83]
	global_load_dwordx4 v[200:203], v169, s[82:83] offset:16
	global_load_dwordx4 v[204:207], v56, s[14:15]
	global_load_dwordx4 v[208:211], v57, s[14:15]
	global_load_dwordx4 v[212:215], v58, s[14:15]
	global_load_dwordx4 v[216:219], v59, s[14:15]
	global_load_dwordx4 v[220:223], v60, s[14:15]
	global_load_dwordx4 v[224:227], v61, s[14:15]
	global_load_dwordx4 v[228:231], v62, s[14:15]
	global_load_dwordx4 v[232:235], v63, s[14:15]
	v_mov_b32_e32 v144, 0xbfb8aa3b
	v_mov_b32_e32 v145, 0xbfb8aa3b
	v_mov_b32_e32 v146, 0x3fb8aa3b
	v_mov_b32_e32 v147, 0x3fb8aa3b
	v_mov_b32_e32 v148, 1.0
	v_mov_b32_e32 v149, 1.0
	s_waitcnt vmcnt(0)
	v_mul_f32_e32 v196, 0xbfb8aa3b, v196
	v_exp_f32_e32 v196, v196
	s_nop 0
	v_add_f32_e32 v236, 1.0, v196
	v_add_f32_e32 v237, -1.0, v236
	v_log_f32_e32 v236, v236
	v_rcp_f32_e32 v238, v237
	v_cmp_eq_f32_e32 vcc, 0, v237
	v_mul_f32_e32 v236, 0x3f317218, v236
	v_mul_f32_e32 v238, v196, v238
	v_mul_f32_e32 v236, v236, v238
	v_cndmask_b32_e32 v196, v236, v196, vcc
	v_mul_f32_e32 v196, 0xc1000000, v196
	v_mul_f32_e32 v197, 0xbfb8aa3b, v197
	v_exp_f32_e32 v197, v197
	s_nop 0
	v_add_f32_e32 v236, 1.0, v197
	v_add_f32_e32 v237, -1.0, v236
	v_log_f32_e32 v236, v236
	v_rcp_f32_e32 v238, v237
	v_cmp_eq_f32_e32 vcc, 0, v237
	v_mul_f32_e32 v236, 0x3f317218, v236
	v_mul_f32_e32 v238, v197, v238
	v_mul_f32_e32 v236, v236, v238
	v_cndmask_b32_e32 v197, v236, v197, vcc
	v_mul_f32_e32 v197, 0xc1000000, v197
	v_mul_f32_e32 v198, 0xbfb8aa3b, v198
	v_exp_f32_e32 v198, v198
	s_nop 0
	v_add_f32_e32 v236, 1.0, v198
	v_add_f32_e32 v237, -1.0, v236
	v_log_f32_e32 v236, v236
	v_rcp_f32_e32 v238, v237
	v_cmp_eq_f32_e32 vcc, 0, v237
	v_mul_f32_e32 v236, 0x3f317218, v236
	v_mul_f32_e32 v238, v198, v238
	v_mul_f32_e32 v236, v236, v238
	v_cndmask_b32_e32 v198, v236, v198, vcc
	v_mul_f32_e32 v198, 0xc1000000, v198
	v_mul_f32_e32 v199, 0xbfb8aa3b, v199
	v_exp_f32_e32 v199, v199
	s_nop 0
	v_add_f32_e32 v236, 1.0, v199
	v_add_f32_e32 v237, -1.0, v236
	v_log_f32_e32 v236, v236
	v_rcp_f32_e32 v238, v237
	v_cmp_eq_f32_e32 vcc, 0, v237
	v_mul_f32_e32 v236, 0x3f317218, v236
	v_mul_f32_e32 v238, v199, v238
	v_mul_f32_e32 v236, v236, v238
	v_cndmask_b32_e32 v199, v236, v199, vcc
	v_mul_f32_e32 v199, 0xc1000000, v199
	v_mul_f32_e32 v200, 0xbfb8aa3b, v200
	v_exp_f32_e32 v200, v200
	s_nop 0
	v_add_f32_e32 v236, 1.0, v200
	v_add_f32_e32 v237, -1.0, v236
	v_log_f32_e32 v236, v236
	v_rcp_f32_e32 v238, v237
	v_cmp_eq_f32_e32 vcc, 0, v237
	v_mul_f32_e32 v236, 0x3f317218, v236
	v_mul_f32_e32 v238, v200, v238
	v_mul_f32_e32 v236, v236, v238
	v_cndmask_b32_e32 v200, v236, v200, vcc
	v_mul_f32_e32 v200, 0xc1000000, v200
	v_mul_f32_e32 v201, 0xbfb8aa3b, v201
	v_exp_f32_e32 v201, v201
	s_nop 0
	v_add_f32_e32 v236, 1.0, v201
	v_add_f32_e32 v237, -1.0, v236
	v_log_f32_e32 v236, v236
	v_rcp_f32_e32 v238, v237
	v_cmp_eq_f32_e32 vcc, 0, v237
	v_mul_f32_e32 v236, 0x3f317218, v236
	v_mul_f32_e32 v238, v201, v238
	v_mul_f32_e32 v236, v236, v238
	v_cndmask_b32_e32 v201, v236, v201, vcc
	v_mul_f32_e32 v201, 0xc1000000, v201
	v_mul_f32_e32 v202, 0xbfb8aa3b, v202
	v_exp_f32_e32 v202, v202
	s_nop 0
	v_add_f32_e32 v236, 1.0, v202
	v_add_f32_e32 v237, -1.0, v236
	v_log_f32_e32 v236, v236
	v_rcp_f32_e32 v238, v237
	v_cmp_eq_f32_e32 vcc, 0, v237
	v_mul_f32_e32 v236, 0x3f317218, v236
	v_mul_f32_e32 v238, v202, v238
	v_mul_f32_e32 v236, v236, v238
	v_cndmask_b32_e32 v202, v236, v202, vcc
	v_mul_f32_e32 v202, 0xc1000000, v202
	v_mul_f32_e32 v203, 0xbfb8aa3b, v203
	v_exp_f32_e32 v203, v203
	s_nop 0
	v_add_f32_e32 v236, 1.0, v203
	v_add_f32_e32 v237, -1.0, v236
	v_log_f32_e32 v236, v236
	v_rcp_f32_e32 v238, v237
	v_cmp_eq_f32_e32 vcc, 0, v237
	v_mul_f32_e32 v236, 0x3f317218, v236
	v_mul_f32_e32 v238, v203, v238
	v_mul_f32_e32 v236, v236, v238
	v_cndmask_b32_e32 v203, v236, v203, vcc
	v_mul_f32_e32 v203, 0xc1000000, v203
	v_mul_f32_e32 v180, 0xbfb8aa3b, v180
	v_mul_f32_e32 v188, 0xbfb8aa3b, v188
	v_mul_f32_e32 v181, 0xbfb8aa3b, v181
	v_mul_f32_e32 v189, 0xbfb8aa3b, v189
	v_mul_f32_e32 v182, 0xbfb8aa3b, v182
	v_mul_f32_e32 v190, 0xbfb8aa3b, v190
	v_mul_f32_e32 v183, 0xbfb8aa3b, v183
	v_mul_f32_e32 v191, 0xbfb8aa3b, v191
	v_mul_f32_e32 v184, 0xbfb8aa3b, v184
	v_mul_f32_e32 v192, 0xbfb8aa3b, v192
	v_mul_f32_e32 v185, 0xbfb8aa3b, v185
	v_mul_f32_e32 v193, 0xbfb8aa3b, v193
	v_mul_f32_e32 v186, 0xbfb8aa3b, v186
	v_mul_f32_e32 v194, 0xbfb8aa3b, v194
	v_mul_f32_e32 v187, 0xbfb8aa3b, v187
	v_mul_f32_e32 v195, 0xbfb8aa3b, v195
	v_cmp_eq_u32_e32 vcc, 0, v165
	s_and_b32 s23, s8, 7
	s_lshr_b32 s27, s33, 2
	s_or_b32 s23, s23, s27
	s_cmp_eq_u32 s23, 0
	s_cselect_b64 vcc, vcc, 0
	v_pk_fma_f32 v[140:141], v[140:141], v[144:145], v[180:181]
	v_pk_fma_f32 v[132:133], v[132:133], v[144:145], v[184:185]
	v_pk_fma_f32 v[142:143], v[142:143], v[144:145], v[182:183]
	v_pk_fma_f32 v[134:135], v[134:135], v[144:145], v[186:187]
	v_pk_fma_f32 v[136:137], v[136:137], v[144:145], v[188:189]
	v_pk_fma_f32 v[128:129], v[128:129], v[144:145], v[192:193]
	v_pk_fma_f32 v[138:139], v[138:139], v[144:145], v[190:191]
	v_pk_fma_f32 v[130:131], v[130:131], v[144:145], v[194:195]
	v_exp_f32_e32 v140, v140
	v_exp_f32_e32 v132, v132
	v_exp_f32_e32 v141, v141
	v_exp_f32_e32 v133, v133
	v_exp_f32_e32 v142, v142
	v_exp_f32_e32 v134, v134
	v_exp_f32_e32 v143, v143
	v_exp_f32_e32 v135, v135
	v_exp_f32_e32 v136, v136
	v_exp_f32_e32 v128, v128
	v_exp_f32_e32 v137, v137
	v_exp_f32_e32 v129, v129
	v_exp_f32_e32 v138, v138
	v_exp_f32_e32 v130, v130
	v_exp_f32_e32 v139, v139
	v_exp_f32_e32 v131, v131
	s_nop 0
	s_nop 0
	v_pk_add_f32 v[140:141], v[140:141], v[148:149]
	v_pk_add_f32 v[132:133], v[132:133], v[148:149]
	v_pk_add_f32 v[142:143], v[142:143], v[148:149]
	v_pk_add_f32 v[134:135], v[134:135], v[148:149]
	v_pk_add_f32 v[136:137], v[136:137], v[148:149]
	v_pk_add_f32 v[128:129], v[128:129], v[148:149]
	v_pk_add_f32 v[138:139], v[138:139], v[148:149]
	v_pk_add_f32 v[130:131], v[130:131], v[148:149]
	v_rcp_f32_e32 v140, v140
	v_rcp_f32_e32 v132, v132
	v_rcp_f32_e32 v141, v141
	v_rcp_f32_e32 v133, v133
	v_rcp_f32_e32 v142, v142
	v_rcp_f32_e32 v134, v134
	v_rcp_f32_e32 v143, v143
	v_rcp_f32_e32 v135, v135
	v_rcp_f32_e32 v136, v136
	v_rcp_f32_e32 v128, v128
	v_rcp_f32_e32 v137, v137
	v_rcp_f32_e32 v129, v129
	v_rcp_f32_e32 v138, v138
	v_rcp_f32_e32 v130, v130
	v_rcp_f32_e32 v139, v139
	v_rcp_f32_e32 v131, v131
	s_nop 0
	s_nop 0
	v_pk_mul_f32 v[140:141], v[140:141], v[196:197]
	v_pk_mul_f32 v[132:133], v[132:133], v[200:201]
	v_pk_mul_f32 v[142:143], v[142:143], v[198:199]
	v_pk_mul_f32 v[134:135], v[134:135], v[202:203]
	v_pk_mul_f32 v[236:237], v[140:141], v[146:147]
	v_pk_mul_f32 v[240:241], v[132:133], v[146:147]
	v_pk_mul_f32 v[238:239], v[142:143], v[146:147]
	v_pk_mul_f32 v[242:243], v[134:135], v[146:147]
	v_exp_f32_e32 v236, v236
	v_exp_f32_e32 v240, v240
	v_exp_f32_e32 v237, v237
	v_exp_f32_e32 v241, v241
	v_exp_f32_e32 v238, v238
	v_exp_f32_e32 v242, v242
	v_exp_f32_e32 v239, v239
	v_exp_f32_e32 v243, v243
	s_nop 0
	s_nop 0
	v_pk_fma_f32 v[236:237], v[236:237], v[236:237], v[148:149] neg_lo:[1,0,0] neg_hi:[1,0,0]
	v_pk_fma_f32 v[240:241], v[240:241], v[240:241], v[148:149] neg_lo:[1,0,0] neg_hi:[1,0,0]
	v_pk_fma_f32 v[238:239], v[238:239], v[238:239], v[148:149] neg_lo:[1,0,0] neg_hi:[1,0,0]
	v_pk_fma_f32 v[242:243], v[242:243], v[242:243], v[148:149] neg_lo:[1,0,0] neg_hi:[1,0,0]
	v_max_f32_e32 v236, 0, v236
	v_max_f32_e32 v240, 0, v240
	v_max_f32_e32 v237, 0, v237
	v_max_f32_e32 v241, 0, v241
	v_max_f32_e32 v238, 0, v238
	v_max_f32_e32 v242, 0, v242
	v_max_f32_e32 v239, 0, v239
	v_max_f32_e32 v243, 0, v243
	v_sqrt_f32_e32 v236, v236
	v_sqrt_f32_e32 v240, v240
	v_sqrt_f32_e32 v237, v237
	v_sqrt_f32_e32 v241, v241
	v_sqrt_f32_e32 v238, v238
	v_sqrt_f32_e32 v242, v242
	v_sqrt_f32_e32 v239, v239
	v_sqrt_f32_e32 v243, v243
	s_nop 0
	s_nop 0
	v_cndmask_b32_e64 v236, v236, 1.0, vcc
	v_cndmask_b32_e64 v240, v240, 1.0, vcc
	v_cndmask_b32_e64 v237, v237, 1.0, vcc
	v_cndmask_b32_e64 v241, v241, 1.0, vcc
	v_cndmask_b32_e64 v238, v238, 1.0, vcc
	v_cndmask_b32_e64 v242, v242, 1.0, vcc
	v_cndmask_b32_e64 v239, v239, 1.0, vcc
	v_cndmask_b32_e64 v243, v243, 1.0, vcc
	v_lshlrev_b32_e32 v244, 16, v204
	v_lshlrev_b32_e32 v248, 16, v206
	v_and_b32_e32 v245, 0xffff0000, v204
	v_and_b32_e32 v249, 0xffff0000, v206
	v_lshlrev_b32_e32 v246, 16, v205
	v_lshlrev_b32_e32 v250, 16, v207
	v_and_b32_e32 v247, 0xffff0000, v205
	v_and_b32_e32 v251, 0xffff0000, v207
	v_pk_mul_f32 v[136:137], v[136:137], v[236:237]
	v_pk_mul_f32 v[128:129], v[128:129], v[240:241]
	v_pk_mul_f32 v[138:139], v[138:139], v[238:239]
	v_pk_mul_f32 v[130:131], v[130:131], v[242:243]
	v_pk_mul_f32 v[136:137], v[136:137], v[244:245]
	v_pk_mul_f32 v[128:129], v[128:129], v[248:249]
	v_pk_mul_f32 v[138:139], v[138:139], v[246:247]
	v_pk_mul_f32 v[130:131], v[130:131], v[250:251]
	v_cvt_pk_bf16_f32 v140, v140, v141
	v_cvt_pk_bf16_f32 v141, v142, v143
	v_cvt_pk_bf16_f32 v142, v132, v133
	v_cvt_pk_bf16_f32 v143, v134, v135
	global_store_dwordx4 v56, v[140:143], s[16:17]
	v_cvt_pk_bf16_f32 v136, v136, v137
	v_cvt_pk_bf16_f32 v137, v138, v139
	v_cvt_pk_bf16_f32 v138, v128, v129
	v_cvt_pk_bf16_f32 v139, v130, v131
	global_store_dwordx4 v56, v[136:139], s[18:19]
	v_pk_fma_f32 v[124:125], v[124:125], v[144:145], v[180:181]
	v_pk_fma_f32 v[116:117], v[116:117], v[144:145], v[184:185]
	v_pk_fma_f32 v[126:127], v[126:127], v[144:145], v[182:183]
	v_pk_fma_f32 v[118:119], v[118:119], v[144:145], v[186:187]
	v_pk_fma_f32 v[120:121], v[120:121], v[144:145], v[188:189]
	v_pk_fma_f32 v[112:113], v[112:113], v[144:145], v[192:193]
	v_pk_fma_f32 v[122:123], v[122:123], v[144:145], v[190:191]
	v_pk_fma_f32 v[114:115], v[114:115], v[144:145], v[194:195]
	v_exp_f32_e32 v124, v124
	v_exp_f32_e32 v116, v116
	v_exp_f32_e32 v125, v125
	v_exp_f32_e32 v117, v117
	v_exp_f32_e32 v126, v126
	v_exp_f32_e32 v118, v118
	v_exp_f32_e32 v127, v127
	v_exp_f32_e32 v119, v119
	v_exp_f32_e32 v120, v120
	v_exp_f32_e32 v112, v112
	v_exp_f32_e32 v121, v121
	v_exp_f32_e32 v113, v113
	v_exp_f32_e32 v122, v122
	v_exp_f32_e32 v114, v114
	v_exp_f32_e32 v123, v123
	v_exp_f32_e32 v115, v115
	s_nop 0
	s_nop 0
	v_pk_add_f32 v[124:125], v[124:125], v[148:149]
	v_pk_add_f32 v[116:117], v[116:117], v[148:149]
	v_pk_add_f32 v[126:127], v[126:127], v[148:149]
	v_pk_add_f32 v[118:119], v[118:119], v[148:149]
	v_pk_add_f32 v[120:121], v[120:121], v[148:149]
	v_pk_add_f32 v[112:113], v[112:113], v[148:149]
	v_pk_add_f32 v[122:123], v[122:123], v[148:149]
	v_pk_add_f32 v[114:115], v[114:115], v[148:149]
	v_rcp_f32_e32 v124, v124
	v_rcp_f32_e32 v116, v116
	v_rcp_f32_e32 v125, v125
	v_rcp_f32_e32 v117, v117
	v_rcp_f32_e32 v126, v126
	v_rcp_f32_e32 v118, v118
	v_rcp_f32_e32 v127, v127
	v_rcp_f32_e32 v119, v119
	v_rcp_f32_e32 v120, v120
	v_rcp_f32_e32 v112, v112
	v_rcp_f32_e32 v121, v121
	v_rcp_f32_e32 v113, v113
	v_rcp_f32_e32 v122, v122
	v_rcp_f32_e32 v114, v114
	v_rcp_f32_e32 v123, v123
	v_rcp_f32_e32 v115, v115
	s_nop 0
	s_nop 0
	v_pk_mul_f32 v[124:125], v[124:125], v[196:197]
	v_pk_mul_f32 v[116:117], v[116:117], v[200:201]
	v_pk_mul_f32 v[126:127], v[126:127], v[198:199]
	v_pk_mul_f32 v[118:119], v[118:119], v[202:203]
	v_pk_mul_f32 v[236:237], v[124:125], v[146:147]
	v_pk_mul_f32 v[240:241], v[116:117], v[146:147]
	v_pk_mul_f32 v[238:239], v[126:127], v[146:147]
	v_pk_mul_f32 v[242:243], v[118:119], v[146:147]
	v_exp_f32_e32 v236, v236
	v_exp_f32_e32 v240, v240
	v_exp_f32_e32 v237, v237
	v_exp_f32_e32 v241, v241
	v_exp_f32_e32 v238, v238
	v_exp_f32_e32 v242, v242
	v_exp_f32_e32 v239, v239
	v_exp_f32_e32 v243, v243
	s_nop 0
	s_nop 0
	v_pk_fma_f32 v[236:237], v[236:237], v[236:237], v[148:149] neg_lo:[1,0,0] neg_hi:[1,0,0]
	v_pk_fma_f32 v[240:241], v[240:241], v[240:241], v[148:149] neg_lo:[1,0,0] neg_hi:[1,0,0]
	v_pk_fma_f32 v[238:239], v[238:239], v[238:239], v[148:149] neg_lo:[1,0,0] neg_hi:[1,0,0]
	v_pk_fma_f32 v[242:243], v[242:243], v[242:243], v[148:149] neg_lo:[1,0,0] neg_hi:[1,0,0]
	v_max_f32_e32 v236, 0, v236
	v_max_f32_e32 v240, 0, v240
	v_max_f32_e32 v237, 0, v237
	v_max_f32_e32 v241, 0, v241
	v_max_f32_e32 v238, 0, v238
	v_max_f32_e32 v242, 0, v242
	v_max_f32_e32 v239, 0, v239
	v_max_f32_e32 v243, 0, v243
	v_sqrt_f32_e32 v236, v236
	v_sqrt_f32_e32 v240, v240
	v_sqrt_f32_e32 v237, v237
	v_sqrt_f32_e32 v241, v241
	v_sqrt_f32_e32 v238, v238
	v_sqrt_f32_e32 v242, v242
	v_sqrt_f32_e32 v239, v239
	v_sqrt_f32_e32 v243, v243
	s_nop 0
	s_nop 0
	v_lshlrev_b32_e32 v244, 16, v208
	v_lshlrev_b32_e32 v248, 16, v210
	v_and_b32_e32 v245, 0xffff0000, v208
	v_and_b32_e32 v249, 0xffff0000, v210
	v_lshlrev_b32_e32 v246, 16, v209
	v_lshlrev_b32_e32 v250, 16, v211
	v_and_b32_e32 v247, 0xffff0000, v209
	v_and_b32_e32 v251, 0xffff0000, v211
	v_pk_mul_f32 v[120:121], v[120:121], v[236:237]
	v_pk_mul_f32 v[112:113], v[112:113], v[240:241]
	v_pk_mul_f32 v[122:123], v[122:123], v[238:239]
	v_pk_mul_f32 v[114:115], v[114:115], v[242:243]
	v_pk_mul_f32 v[120:121], v[120:121], v[244:245]
	v_pk_mul_f32 v[112:113], v[112:113], v[248:249]
	v_pk_mul_f32 v[122:123], v[122:123], v[246:247]
	v_pk_mul_f32 v[114:115], v[114:115], v[250:251]
	v_cvt_pk_bf16_f32 v124, v124, v125
	v_cvt_pk_bf16_f32 v125, v126, v127
	v_cvt_pk_bf16_f32 v126, v116, v117
	v_cvt_pk_bf16_f32 v127, v118, v119
	global_store_dwordx4 v57, v[124:127], s[16:17]
	v_cvt_pk_bf16_f32 v120, v120, v121
	v_cvt_pk_bf16_f32 v121, v122, v123
	v_cvt_pk_bf16_f32 v122, v112, v113
	v_cvt_pk_bf16_f32 v123, v114, v115
	global_store_dwordx4 v57, v[120:123], s[18:19]
	v_pk_fma_f32 v[108:109], v[108:109], v[144:145], v[180:181]
	v_pk_fma_f32 v[100:101], v[100:101], v[144:145], v[184:185]
	v_pk_fma_f32 v[110:111], v[110:111], v[144:145], v[182:183]
	v_pk_fma_f32 v[102:103], v[102:103], v[144:145], v[186:187]
	v_pk_fma_f32 v[104:105], v[104:105], v[144:145], v[188:189]
	v_pk_fma_f32 v[96:97], v[96:97], v[144:145], v[192:193]
	v_pk_fma_f32 v[106:107], v[106:107], v[144:145], v[190:191]
	v_pk_fma_f32 v[98:99], v[98:99], v[144:145], v[194:195]
	v_exp_f32_e32 v108, v108
	v_exp_f32_e32 v100, v100
	v_exp_f32_e32 v109, v109
	v_exp_f32_e32 v101, v101
	v_exp_f32_e32 v110, v110
	v_exp_f32_e32 v102, v102
	v_exp_f32_e32 v111, v111
	v_exp_f32_e32 v103, v103
	v_exp_f32_e32 v104, v104
	v_exp_f32_e32 v96, v96
	v_exp_f32_e32 v105, v105
	v_exp_f32_e32 v97, v97
	v_exp_f32_e32 v106, v106
	v_exp_f32_e32 v98, v98
	v_exp_f32_e32 v107, v107
	v_exp_f32_e32 v99, v99
	s_nop 0
	s_nop 0
	v_pk_add_f32 v[108:109], v[108:109], v[148:149]
	v_pk_add_f32 v[100:101], v[100:101], v[148:149]
	v_pk_add_f32 v[110:111], v[110:111], v[148:149]
	v_pk_add_f32 v[102:103], v[102:103], v[148:149]
	v_pk_add_f32 v[104:105], v[104:105], v[148:149]
	v_pk_add_f32 v[96:97], v[96:97], v[148:149]
	v_pk_add_f32 v[106:107], v[106:107], v[148:149]
	v_pk_add_f32 v[98:99], v[98:99], v[148:149]
	v_rcp_f32_e32 v108, v108
	v_rcp_f32_e32 v100, v100
	v_rcp_f32_e32 v109, v109
	v_rcp_f32_e32 v101, v101
	v_rcp_f32_e32 v110, v110
	v_rcp_f32_e32 v102, v102
	v_rcp_f32_e32 v111, v111
	v_rcp_f32_e32 v103, v103
	v_rcp_f32_e32 v104, v104
	v_rcp_f32_e32 v96, v96
	v_rcp_f32_e32 v105, v105
	v_rcp_f32_e32 v97, v97
	v_rcp_f32_e32 v106, v106
	v_rcp_f32_e32 v98, v98
	v_rcp_f32_e32 v107, v107
	v_rcp_f32_e32 v99, v99
	s_nop 0
	s_nop 0
	v_pk_mul_f32 v[108:109], v[108:109], v[196:197]
	v_pk_mul_f32 v[100:101], v[100:101], v[200:201]
	v_pk_mul_f32 v[110:111], v[110:111], v[198:199]
	v_pk_mul_f32 v[102:103], v[102:103], v[202:203]
	v_pk_mul_f32 v[236:237], v[108:109], v[146:147]
	v_pk_mul_f32 v[240:241], v[100:101], v[146:147]
	v_pk_mul_f32 v[238:239], v[110:111], v[146:147]
	v_pk_mul_f32 v[242:243], v[102:103], v[146:147]
	v_exp_f32_e32 v236, v236
	v_exp_f32_e32 v240, v240
	v_exp_f32_e32 v237, v237
	v_exp_f32_e32 v241, v241
	v_exp_f32_e32 v238, v238
	v_exp_f32_e32 v242, v242
	v_exp_f32_e32 v239, v239
	v_exp_f32_e32 v243, v243
	s_nop 0
	s_nop 0
	v_pk_fma_f32 v[236:237], v[236:237], v[236:237], v[148:149] neg_lo:[1,0,0] neg_hi:[1,0,0]
	v_pk_fma_f32 v[240:241], v[240:241], v[240:241], v[148:149] neg_lo:[1,0,0] neg_hi:[1,0,0]
	v_pk_fma_f32 v[238:239], v[238:239], v[238:239], v[148:149] neg_lo:[1,0,0] neg_hi:[1,0,0]
	v_pk_fma_f32 v[242:243], v[242:243], v[242:243], v[148:149] neg_lo:[1,0,0] neg_hi:[1,0,0]
	v_max_f32_e32 v236, 0, v236
	v_max_f32_e32 v240, 0, v240
	v_max_f32_e32 v237, 0, v237
	v_max_f32_e32 v241, 0, v241
	v_max_f32_e32 v238, 0, v238
	v_max_f32_e32 v242, 0, v242
	v_max_f32_e32 v239, 0, v239
	v_max_f32_e32 v243, 0, v243
	v_sqrt_f32_e32 v236, v236
	v_sqrt_f32_e32 v240, v240
	v_sqrt_f32_e32 v237, v237
	v_sqrt_f32_e32 v241, v241
	v_sqrt_f32_e32 v238, v238
	v_sqrt_f32_e32 v242, v242
	v_sqrt_f32_e32 v239, v239
	v_sqrt_f32_e32 v243, v243
	s_nop 0
	s_nop 0
	v_lshlrev_b32_e32 v244, 16, v212
	v_lshlrev_b32_e32 v248, 16, v214
	v_and_b32_e32 v245, 0xffff0000, v212
	v_and_b32_e32 v249, 0xffff0000, v214
	v_lshlrev_b32_e32 v246, 16, v213
	v_lshlrev_b32_e32 v250, 16, v215
	v_and_b32_e32 v247, 0xffff0000, v213
	v_and_b32_e32 v251, 0xffff0000, v215
	v_pk_mul_f32 v[104:105], v[104:105], v[236:237]
	v_pk_mul_f32 v[96:97], v[96:97], v[240:241]
	v_pk_mul_f32 v[106:107], v[106:107], v[238:239]
	v_pk_mul_f32 v[98:99], v[98:99], v[242:243]
	v_pk_mul_f32 v[104:105], v[104:105], v[244:245]
	v_pk_mul_f32 v[96:97], v[96:97], v[248:249]
	v_pk_mul_f32 v[106:107], v[106:107], v[246:247]
	v_pk_mul_f32 v[98:99], v[98:99], v[250:251]
	v_cvt_pk_bf16_f32 v108, v108, v109
	v_cvt_pk_bf16_f32 v109, v110, v111
	v_cvt_pk_bf16_f32 v110, v100, v101
	v_cvt_pk_bf16_f32 v111, v102, v103
	global_store_dwordx4 v58, v[108:111], s[16:17]
	v_cvt_pk_bf16_f32 v104, v104, v105
	v_cvt_pk_bf16_f32 v105, v106, v107
	v_cvt_pk_bf16_f32 v106, v96, v97
	v_cvt_pk_bf16_f32 v107, v98, v99
	global_store_dwordx4 v58, v[104:107], s[18:19]
	v_pk_fma_f32 v[92:93], v[92:93], v[144:145], v[180:181]
	v_pk_fma_f32 v[84:85], v[84:85], v[144:145], v[184:185]
	v_pk_fma_f32 v[94:95], v[94:95], v[144:145], v[182:183]
	v_pk_fma_f32 v[86:87], v[86:87], v[144:145], v[186:187]
	v_pk_fma_f32 v[88:89], v[88:89], v[144:145], v[188:189]
	v_pk_fma_f32 v[80:81], v[80:81], v[144:145], v[192:193]
	v_pk_fma_f32 v[90:91], v[90:91], v[144:145], v[190:191]
	v_pk_fma_f32 v[82:83], v[82:83], v[144:145], v[194:195]
	v_exp_f32_e32 v92, v92
	v_exp_f32_e32 v84, v84
	v_exp_f32_e32 v93, v93
	v_exp_f32_e32 v85, v85
	v_exp_f32_e32 v94, v94
	v_exp_f32_e32 v86, v86
	v_exp_f32_e32 v95, v95
	v_exp_f32_e32 v87, v87
	v_exp_f32_e32 v88, v88
	v_exp_f32_e32 v80, v80
	v_exp_f32_e32 v89, v89
	v_exp_f32_e32 v81, v81
	v_exp_f32_e32 v90, v90
	v_exp_f32_e32 v82, v82
	v_exp_f32_e32 v91, v91
	v_exp_f32_e32 v83, v83
	s_nop 0
	s_nop 0
	v_pk_add_f32 v[92:93], v[92:93], v[148:149]
	v_pk_add_f32 v[84:85], v[84:85], v[148:149]
	v_pk_add_f32 v[94:95], v[94:95], v[148:149]
	v_pk_add_f32 v[86:87], v[86:87], v[148:149]
	v_pk_add_f32 v[88:89], v[88:89], v[148:149]
	v_pk_add_f32 v[80:81], v[80:81], v[148:149]
	v_pk_add_f32 v[90:91], v[90:91], v[148:149]
	v_pk_add_f32 v[82:83], v[82:83], v[148:149]
	v_rcp_f32_e32 v92, v92
	v_rcp_f32_e32 v84, v84
	v_rcp_f32_e32 v93, v93
	v_rcp_f32_e32 v85, v85
	v_rcp_f32_e32 v94, v94
	v_rcp_f32_e32 v86, v86
	v_rcp_f32_e32 v95, v95
	v_rcp_f32_e32 v87, v87
	v_rcp_f32_e32 v88, v88
	v_rcp_f32_e32 v80, v80
	v_rcp_f32_e32 v89, v89
	v_rcp_f32_e32 v81, v81
	v_rcp_f32_e32 v90, v90
	v_rcp_f32_e32 v82, v82
	v_rcp_f32_e32 v91, v91
	v_rcp_f32_e32 v83, v83
	s_nop 0
	s_nop 0
	v_pk_mul_f32 v[92:93], v[92:93], v[196:197]
	v_pk_mul_f32 v[84:85], v[84:85], v[200:201]
	v_pk_mul_f32 v[94:95], v[94:95], v[198:199]
	v_pk_mul_f32 v[86:87], v[86:87], v[202:203]
	v_pk_mul_f32 v[236:237], v[92:93], v[146:147]
	v_pk_mul_f32 v[240:241], v[84:85], v[146:147]
	v_pk_mul_f32 v[238:239], v[94:95], v[146:147]
	v_pk_mul_f32 v[242:243], v[86:87], v[146:147]
	v_exp_f32_e32 v236, v236
	v_exp_f32_e32 v240, v240
	v_exp_f32_e32 v237, v237
	v_exp_f32_e32 v241, v241
	v_exp_f32_e32 v238, v238
	v_exp_f32_e32 v242, v242
	v_exp_f32_e32 v239, v239
	v_exp_f32_e32 v243, v243
	s_nop 0
	s_nop 0
	v_pk_fma_f32 v[236:237], v[236:237], v[236:237], v[148:149] neg_lo:[1,0,0] neg_hi:[1,0,0]
	v_pk_fma_f32 v[240:241], v[240:241], v[240:241], v[148:149] neg_lo:[1,0,0] neg_hi:[1,0,0]
	v_pk_fma_f32 v[238:239], v[238:239], v[238:239], v[148:149] neg_lo:[1,0,0] neg_hi:[1,0,0]
	v_pk_fma_f32 v[242:243], v[242:243], v[242:243], v[148:149] neg_lo:[1,0,0] neg_hi:[1,0,0]
	v_max_f32_e32 v236, 0, v236
	v_max_f32_e32 v240, 0, v240
	v_max_f32_e32 v237, 0, v237
	v_max_f32_e32 v241, 0, v241
	v_max_f32_e32 v238, 0, v238
	v_max_f32_e32 v242, 0, v242
	v_max_f32_e32 v239, 0, v239
	v_max_f32_e32 v243, 0, v243
	v_sqrt_f32_e32 v236, v236
	v_sqrt_f32_e32 v240, v240
	v_sqrt_f32_e32 v237, v237
	v_sqrt_f32_e32 v241, v241
	v_sqrt_f32_e32 v238, v238
	v_sqrt_f32_e32 v242, v242
	v_sqrt_f32_e32 v239, v239
	v_sqrt_f32_e32 v243, v243
	s_nop 0
	s_nop 0
	v_lshlrev_b32_e32 v244, 16, v216
	v_lshlrev_b32_e32 v248, 16, v218
	v_and_b32_e32 v245, 0xffff0000, v216
	v_and_b32_e32 v249, 0xffff0000, v218
	v_lshlrev_b32_e32 v246, 16, v217
	v_lshlrev_b32_e32 v250, 16, v219
	v_and_b32_e32 v247, 0xffff0000, v217
	v_and_b32_e32 v251, 0xffff0000, v219
	v_pk_mul_f32 v[88:89], v[88:89], v[236:237]
	v_pk_mul_f32 v[80:81], v[80:81], v[240:241]
	v_pk_mul_f32 v[90:91], v[90:91], v[238:239]
	v_pk_mul_f32 v[82:83], v[82:83], v[242:243]
	v_pk_mul_f32 v[88:89], v[88:89], v[244:245]
	v_pk_mul_f32 v[80:81], v[80:81], v[248:249]
	v_pk_mul_f32 v[90:91], v[90:91], v[246:247]
	v_pk_mul_f32 v[82:83], v[82:83], v[250:251]
	v_cvt_pk_bf16_f32 v92, v92, v93
	v_cvt_pk_bf16_f32 v93, v94, v95
	v_cvt_pk_bf16_f32 v94, v84, v85
	v_cvt_pk_bf16_f32 v95, v86, v87
	global_store_dwordx4 v59, v[92:95], s[16:17]
	v_cvt_pk_bf16_f32 v88, v88, v89
	v_cvt_pk_bf16_f32 v89, v90, v91
	v_cvt_pk_bf16_f32 v90, v80, v81
	v_cvt_pk_bf16_f32 v91, v82, v83
	global_store_dwordx4 v59, v[88:91], s[18:19]
	v_pk_fma_f32 v[76:77], v[76:77], v[144:145], v[180:181]
	v_pk_fma_f32 v[68:69], v[68:69], v[144:145], v[184:185]
	v_pk_fma_f32 v[78:79], v[78:79], v[144:145], v[182:183]
	v_pk_fma_f32 v[70:71], v[70:71], v[144:145], v[186:187]
	v_pk_fma_f32 v[72:73], v[72:73], v[144:145], v[188:189]
	v_pk_fma_f32 v[64:65], v[64:65], v[144:145], v[192:193]
	v_pk_fma_f32 v[74:75], v[74:75], v[144:145], v[190:191]
	v_pk_fma_f32 v[66:67], v[66:67], v[144:145], v[194:195]
	v_exp_f32_e32 v76, v76
	v_exp_f32_e32 v68, v68
	v_exp_f32_e32 v77, v77
	v_exp_f32_e32 v69, v69
	v_exp_f32_e32 v78, v78
	v_exp_f32_e32 v70, v70
	v_exp_f32_e32 v79, v79
	v_exp_f32_e32 v71, v71
	v_exp_f32_e32 v72, v72
	v_exp_f32_e32 v64, v64
	v_exp_f32_e32 v73, v73
	v_exp_f32_e32 v65, v65
	v_exp_f32_e32 v74, v74
	v_exp_f32_e32 v66, v66
	v_exp_f32_e32 v75, v75
	v_exp_f32_e32 v67, v67
	s_nop 0
	s_nop 0
	v_pk_add_f32 v[76:77], v[76:77], v[148:149]
	v_pk_add_f32 v[68:69], v[68:69], v[148:149]
	v_pk_add_f32 v[78:79], v[78:79], v[148:149]
	v_pk_add_f32 v[70:71], v[70:71], v[148:149]
	v_pk_add_f32 v[72:73], v[72:73], v[148:149]
	v_pk_add_f32 v[64:65], v[64:65], v[148:149]
	v_pk_add_f32 v[74:75], v[74:75], v[148:149]
	v_pk_add_f32 v[66:67], v[66:67], v[148:149]
	v_rcp_f32_e32 v76, v76
	v_rcp_f32_e32 v68, v68
	v_rcp_f32_e32 v77, v77
	v_rcp_f32_e32 v69, v69
	v_rcp_f32_e32 v78, v78
	v_rcp_f32_e32 v70, v70
	v_rcp_f32_e32 v79, v79
	v_rcp_f32_e32 v71, v71
	v_rcp_f32_e32 v72, v72
	v_rcp_f32_e32 v64, v64
	v_rcp_f32_e32 v73, v73
	v_rcp_f32_e32 v65, v65
	v_rcp_f32_e32 v74, v74
	v_rcp_f32_e32 v66, v66
	v_rcp_f32_e32 v75, v75
	v_rcp_f32_e32 v67, v67
	s_nop 0
	s_nop 0
	v_pk_mul_f32 v[76:77], v[76:77], v[196:197]
	v_pk_mul_f32 v[68:69], v[68:69], v[200:201]
	v_pk_mul_f32 v[78:79], v[78:79], v[198:199]
	v_pk_mul_f32 v[70:71], v[70:71], v[202:203]
	v_pk_mul_f32 v[236:237], v[76:77], v[146:147]
	v_pk_mul_f32 v[240:241], v[68:69], v[146:147]
	v_pk_mul_f32 v[238:239], v[78:79], v[146:147]
	v_pk_mul_f32 v[242:243], v[70:71], v[146:147]
	v_exp_f32_e32 v236, v236
	v_exp_f32_e32 v240, v240
	v_exp_f32_e32 v237, v237
	v_exp_f32_e32 v241, v241
	v_exp_f32_e32 v238, v238
	v_exp_f32_e32 v242, v242
	v_exp_f32_e32 v239, v239
	v_exp_f32_e32 v243, v243
	s_nop 0
	s_nop 0
	v_pk_fma_f32 v[236:237], v[236:237], v[236:237], v[148:149] neg_lo:[1,0,0] neg_hi:[1,0,0]
	v_pk_fma_f32 v[240:241], v[240:241], v[240:241], v[148:149] neg_lo:[1,0,0] neg_hi:[1,0,0]
	v_pk_fma_f32 v[238:239], v[238:239], v[238:239], v[148:149] neg_lo:[1,0,0] neg_hi:[1,0,0]
	v_pk_fma_f32 v[242:243], v[242:243], v[242:243], v[148:149] neg_lo:[1,0,0] neg_hi:[1,0,0]
	v_max_f32_e32 v236, 0, v236
	v_max_f32_e32 v240, 0, v240
	v_max_f32_e32 v237, 0, v237
	v_max_f32_e32 v241, 0, v241
	v_max_f32_e32 v238, 0, v238
	v_max_f32_e32 v242, 0, v242
	v_max_f32_e32 v239, 0, v239
	v_max_f32_e32 v243, 0, v243
	v_sqrt_f32_e32 v236, v236
	v_sqrt_f32_e32 v240, v240
	v_sqrt_f32_e32 v237, v237
	v_sqrt_f32_e32 v241, v241
	v_sqrt_f32_e32 v238, v238
	v_sqrt_f32_e32 v242, v242
	v_sqrt_f32_e32 v239, v239
	v_sqrt_f32_e32 v243, v243
	s_nop 0
	s_nop 0
	v_lshlrev_b32_e32 v244, 16, v220
	v_lshlrev_b32_e32 v248, 16, v222
	v_and_b32_e32 v245, 0xffff0000, v220
	v_and_b32_e32 v249, 0xffff0000, v222
	v_lshlrev_b32_e32 v246, 16, v221
	v_lshlrev_b32_e32 v250, 16, v223
	v_and_b32_e32 v247, 0xffff0000, v221
	v_and_b32_e32 v251, 0xffff0000, v223
	v_pk_mul_f32 v[72:73], v[72:73], v[236:237]
	v_pk_mul_f32 v[64:65], v[64:65], v[240:241]
	v_pk_mul_f32 v[74:75], v[74:75], v[238:239]
	v_pk_mul_f32 v[66:67], v[66:67], v[242:243]
	v_pk_mul_f32 v[72:73], v[72:73], v[244:245]
	v_pk_mul_f32 v[64:65], v[64:65], v[248:249]
	v_pk_mul_f32 v[74:75], v[74:75], v[246:247]
	v_pk_mul_f32 v[66:67], v[66:67], v[250:251]
	v_cvt_pk_bf16_f32 v76, v76, v77
	v_cvt_pk_bf16_f32 v77, v78, v79
	v_cvt_pk_bf16_f32 v78, v68, v69
	v_cvt_pk_bf16_f32 v79, v70, v71
	global_store_dwordx4 v60, v[76:79], s[16:17]
	v_cvt_pk_bf16_f32 v72, v72, v73
	v_cvt_pk_bf16_f32 v73, v74, v75
	v_cvt_pk_bf16_f32 v74, v64, v65
	v_cvt_pk_bf16_f32 v75, v66, v67
	global_store_dwordx4 v60, v[72:75], s[18:19]
	v_pk_fma_f32 v[52:53], v[52:53], v[144:145], v[180:181]
	v_pk_fma_f32 v[36:37], v[36:37], v[144:145], v[184:185]
	v_pk_fma_f32 v[54:55], v[54:55], v[144:145], v[182:183]
	v_pk_fma_f32 v[38:39], v[38:39], v[144:145], v[186:187]
	v_pk_fma_f32 v[48:49], v[48:49], v[144:145], v[188:189]
	v_pk_fma_f32 v[32:33], v[32:33], v[144:145], v[192:193]
	v_pk_fma_f32 v[50:51], v[50:51], v[144:145], v[190:191]
	v_pk_fma_f32 v[34:35], v[34:35], v[144:145], v[194:195]
	v_exp_f32_e32 v52, v52
	v_exp_f32_e32 v36, v36
	v_exp_f32_e32 v53, v53
	v_exp_f32_e32 v37, v37
	v_exp_f32_e32 v54, v54
	v_exp_f32_e32 v38, v38
	v_exp_f32_e32 v55, v55
	v_exp_f32_e32 v39, v39
	v_exp_f32_e32 v48, v48
	v_exp_f32_e32 v32, v32
	v_exp_f32_e32 v49, v49
	v_exp_f32_e32 v33, v33
	v_exp_f32_e32 v50, v50
	v_exp_f32_e32 v34, v34
	v_exp_f32_e32 v51, v51
	v_exp_f32_e32 v35, v35
	s_nop 0
	s_nop 0
	v_pk_add_f32 v[52:53], v[52:53], v[148:149]
	v_pk_add_f32 v[36:37], v[36:37], v[148:149]
	v_pk_add_f32 v[54:55], v[54:55], v[148:149]
	v_pk_add_f32 v[38:39], v[38:39], v[148:149]
	v_pk_add_f32 v[48:49], v[48:49], v[148:149]
	v_pk_add_f32 v[32:33], v[32:33], v[148:149]
	v_pk_add_f32 v[50:51], v[50:51], v[148:149]
	v_pk_add_f32 v[34:35], v[34:35], v[148:149]
	v_rcp_f32_e32 v52, v52
	v_rcp_f32_e32 v36, v36
	v_rcp_f32_e32 v53, v53
	v_rcp_f32_e32 v37, v37
	v_rcp_f32_e32 v54, v54
	v_rcp_f32_e32 v38, v38
	v_rcp_f32_e32 v55, v55
	v_rcp_f32_e32 v39, v39
	v_rcp_f32_e32 v48, v48
	v_rcp_f32_e32 v32, v32
	v_rcp_f32_e32 v49, v49
	v_rcp_f32_e32 v33, v33
	v_rcp_f32_e32 v50, v50
	v_rcp_f32_e32 v34, v34
	v_rcp_f32_e32 v51, v51
	v_rcp_f32_e32 v35, v35
	s_nop 0
	s_nop 0
	v_pk_mul_f32 v[52:53], v[52:53], v[196:197]
	v_pk_mul_f32 v[36:37], v[36:37], v[200:201]
	v_pk_mul_f32 v[54:55], v[54:55], v[198:199]
	v_pk_mul_f32 v[38:39], v[38:39], v[202:203]
	v_pk_mul_f32 v[236:237], v[52:53], v[146:147]
	v_pk_mul_f32 v[240:241], v[36:37], v[146:147]
	v_pk_mul_f32 v[238:239], v[54:55], v[146:147]
	v_pk_mul_f32 v[242:243], v[38:39], v[146:147]
	v_exp_f32_e32 v236, v236
	v_exp_f32_e32 v240, v240
	v_exp_f32_e32 v237, v237
	v_exp_f32_e32 v241, v241
	v_exp_f32_e32 v238, v238
	v_exp_f32_e32 v242, v242
	v_exp_f32_e32 v239, v239
	v_exp_f32_e32 v243, v243
	s_nop 0
	s_nop 0
	v_pk_fma_f32 v[236:237], v[236:237], v[236:237], v[148:149] neg_lo:[1,0,0] neg_hi:[1,0,0]
	v_pk_fma_f32 v[240:241], v[240:241], v[240:241], v[148:149] neg_lo:[1,0,0] neg_hi:[1,0,0]
	v_pk_fma_f32 v[238:239], v[238:239], v[238:239], v[148:149] neg_lo:[1,0,0] neg_hi:[1,0,0]
	v_pk_fma_f32 v[242:243], v[242:243], v[242:243], v[148:149] neg_lo:[1,0,0] neg_hi:[1,0,0]
	v_max_f32_e32 v236, 0, v236
	v_max_f32_e32 v240, 0, v240
	v_max_f32_e32 v237, 0, v237
	v_max_f32_e32 v241, 0, v241
	v_max_f32_e32 v238, 0, v238
	v_max_f32_e32 v242, 0, v242
	v_max_f32_e32 v239, 0, v239
	v_max_f32_e32 v243, 0, v243
	v_sqrt_f32_e32 v236, v236
	v_sqrt_f32_e32 v240, v240
	v_sqrt_f32_e32 v237, v237
	v_sqrt_f32_e32 v241, v241
	v_sqrt_f32_e32 v238, v238
	v_sqrt_f32_e32 v242, v242
	v_sqrt_f32_e32 v239, v239
	v_sqrt_f32_e32 v243, v243
	s_nop 0
	s_nop 0
	v_lshlrev_b32_e32 v244, 16, v224
	v_lshlrev_b32_e32 v248, 16, v226
	v_and_b32_e32 v245, 0xffff0000, v224
	v_and_b32_e32 v249, 0xffff0000, v226
	v_lshlrev_b32_e32 v246, 16, v225
	v_lshlrev_b32_e32 v250, 16, v227
	v_and_b32_e32 v247, 0xffff0000, v225
	v_and_b32_e32 v251, 0xffff0000, v227
	v_pk_mul_f32 v[48:49], v[48:49], v[236:237]
	v_pk_mul_f32 v[32:33], v[32:33], v[240:241]
	v_pk_mul_f32 v[50:51], v[50:51], v[238:239]
	v_pk_mul_f32 v[34:35], v[34:35], v[242:243]
	v_pk_mul_f32 v[48:49], v[48:49], v[244:245]
	v_pk_mul_f32 v[32:33], v[32:33], v[248:249]
	v_pk_mul_f32 v[50:51], v[50:51], v[246:247]
	v_pk_mul_f32 v[34:35], v[34:35], v[250:251]
	v_cvt_pk_bf16_f32 v52, v52, v53
	v_cvt_pk_bf16_f32 v53, v54, v55
	v_cvt_pk_bf16_f32 v54, v36, v37
	v_cvt_pk_bf16_f32 v55, v38, v39
	global_store_dwordx4 v61, v[52:55], s[16:17]
	v_cvt_pk_bf16_f32 v48, v48, v49
	v_cvt_pk_bf16_f32 v49, v50, v51
	v_cvt_pk_bf16_f32 v50, v32, v33
	v_cvt_pk_bf16_f32 v51, v34, v35
	global_store_dwordx4 v61, v[48:51], s[18:19]
	v_pk_fma_f32 v[28:29], v[28:29], v[144:145], v[180:181]
	v_pk_fma_f32 v[20:21], v[20:21], v[144:145], v[184:185]
	v_pk_fma_f32 v[30:31], v[30:31], v[144:145], v[182:183]
	v_pk_fma_f32 v[22:23], v[22:23], v[144:145], v[186:187]
	v_pk_fma_f32 v[24:25], v[24:25], v[144:145], v[188:189]
	v_pk_fma_f32 v[16:17], v[16:17], v[144:145], v[192:193]
	v_pk_fma_f32 v[26:27], v[26:27], v[144:145], v[190:191]
	v_pk_fma_f32 v[18:19], v[18:19], v[144:145], v[194:195]
	v_exp_f32_e32 v28, v28
	v_exp_f32_e32 v20, v20
	v_exp_f32_e32 v29, v29
	v_exp_f32_e32 v21, v21
	v_exp_f32_e32 v30, v30
	v_exp_f32_e32 v22, v22
	v_exp_f32_e32 v31, v31
	v_exp_f32_e32 v23, v23
	v_exp_f32_e32 v24, v24
	v_exp_f32_e32 v16, v16
	v_exp_f32_e32 v25, v25
	v_exp_f32_e32 v17, v17
	v_exp_f32_e32 v26, v26
	v_exp_f32_e32 v18, v18
	v_exp_f32_e32 v27, v27
	v_exp_f32_e32 v19, v19
	s_nop 0
	s_nop 0
	v_pk_add_f32 v[28:29], v[28:29], v[148:149]
	v_pk_add_f32 v[20:21], v[20:21], v[148:149]
	v_pk_add_f32 v[30:31], v[30:31], v[148:149]
	v_pk_add_f32 v[22:23], v[22:23], v[148:149]
	v_pk_add_f32 v[24:25], v[24:25], v[148:149]
	v_pk_add_f32 v[16:17], v[16:17], v[148:149]
	v_pk_add_f32 v[26:27], v[26:27], v[148:149]
	v_pk_add_f32 v[18:19], v[18:19], v[148:149]
	v_rcp_f32_e32 v28, v28
	v_rcp_f32_e32 v20, v20
	v_rcp_f32_e32 v29, v29
	v_rcp_f32_e32 v21, v21
	v_rcp_f32_e32 v30, v30
	v_rcp_f32_e32 v22, v22
	v_rcp_f32_e32 v31, v31
	v_rcp_f32_e32 v23, v23
	v_rcp_f32_e32 v24, v24
	v_rcp_f32_e32 v16, v16
	v_rcp_f32_e32 v25, v25
	v_rcp_f32_e32 v17, v17
	v_rcp_f32_e32 v26, v26
	v_rcp_f32_e32 v18, v18
	v_rcp_f32_e32 v27, v27
	v_rcp_f32_e32 v19, v19
	s_nop 0
	s_nop 0
	v_pk_mul_f32 v[28:29], v[28:29], v[196:197]
	v_pk_mul_f32 v[20:21], v[20:21], v[200:201]
	v_pk_mul_f32 v[30:31], v[30:31], v[198:199]
	v_pk_mul_f32 v[22:23], v[22:23], v[202:203]
	v_pk_mul_f32 v[236:237], v[28:29], v[146:147]
	v_pk_mul_f32 v[240:241], v[20:21], v[146:147]
	v_pk_mul_f32 v[238:239], v[30:31], v[146:147]
	v_pk_mul_f32 v[242:243], v[22:23], v[146:147]
	v_exp_f32_e32 v236, v236
	v_exp_f32_e32 v240, v240
	v_exp_f32_e32 v237, v237
	v_exp_f32_e32 v241, v241
	v_exp_f32_e32 v238, v238
	v_exp_f32_e32 v242, v242
	v_exp_f32_e32 v239, v239
	v_exp_f32_e32 v243, v243
	s_nop 0
	s_nop 0
	v_pk_fma_f32 v[236:237], v[236:237], v[236:237], v[148:149] neg_lo:[1,0,0] neg_hi:[1,0,0]
	v_pk_fma_f32 v[240:241], v[240:241], v[240:241], v[148:149] neg_lo:[1,0,0] neg_hi:[1,0,0]
	v_pk_fma_f32 v[238:239], v[238:239], v[238:239], v[148:149] neg_lo:[1,0,0] neg_hi:[1,0,0]
	v_pk_fma_f32 v[242:243], v[242:243], v[242:243], v[148:149] neg_lo:[1,0,0] neg_hi:[1,0,0]
	v_max_f32_e32 v236, 0, v236
	v_max_f32_e32 v240, 0, v240
	v_max_f32_e32 v237, 0, v237
	v_max_f32_e32 v241, 0, v241
	v_max_f32_e32 v238, 0, v238
	v_max_f32_e32 v242, 0, v242
	v_max_f32_e32 v239, 0, v239
	v_max_f32_e32 v243, 0, v243
	v_sqrt_f32_e32 v236, v236
	v_sqrt_f32_e32 v240, v240
	v_sqrt_f32_e32 v237, v237
	v_sqrt_f32_e32 v241, v241
	v_sqrt_f32_e32 v238, v238
	v_sqrt_f32_e32 v242, v242
	v_sqrt_f32_e32 v239, v239
	v_sqrt_f32_e32 v243, v243
	s_nop 0
	s_nop 0
	v_lshlrev_b32_e32 v244, 16, v228
	v_lshlrev_b32_e32 v248, 16, v230
	v_and_b32_e32 v245, 0xffff0000, v228
	v_and_b32_e32 v249, 0xffff0000, v230
	v_lshlrev_b32_e32 v246, 16, v229
	v_lshlrev_b32_e32 v250, 16, v231
	v_and_b32_e32 v247, 0xffff0000, v229
	v_and_b32_e32 v251, 0xffff0000, v231
	v_pk_mul_f32 v[24:25], v[24:25], v[236:237]
	v_pk_mul_f32 v[16:17], v[16:17], v[240:241]
	v_pk_mul_f32 v[26:27], v[26:27], v[238:239]
	v_pk_mul_f32 v[18:19], v[18:19], v[242:243]
	v_pk_mul_f32 v[24:25], v[24:25], v[244:245]
	v_pk_mul_f32 v[16:17], v[16:17], v[248:249]
	v_pk_mul_f32 v[26:27], v[26:27], v[246:247]
	v_pk_mul_f32 v[18:19], v[18:19], v[250:251]
	v_cvt_pk_bf16_f32 v28, v28, v29
	v_cvt_pk_bf16_f32 v29, v30, v31
	v_cvt_pk_bf16_f32 v30, v20, v21
	v_cvt_pk_bf16_f32 v31, v22, v23
	global_store_dwordx4 v62, v[28:31], s[16:17]
	v_cvt_pk_bf16_f32 v24, v24, v25
	v_cvt_pk_bf16_f32 v25, v26, v27
	v_cvt_pk_bf16_f32 v26, v16, v17
	v_cvt_pk_bf16_f32 v27, v18, v19
	global_store_dwordx4 v62, v[24:27], s[18:19]
	v_pk_fma_f32 v[12:13], v[12:13], v[144:145], v[180:181]
	v_pk_fma_f32 v[4:5], v[4:5], v[144:145], v[184:185]
	v_pk_fma_f32 v[14:15], v[14:15], v[144:145], v[182:183]
	v_pk_fma_f32 v[6:7], v[6:7], v[144:145], v[186:187]
	v_pk_fma_f32 v[8:9], v[8:9], v[144:145], v[188:189]
	v_pk_fma_f32 v[0:1], v[0:1], v[144:145], v[192:193]
	v_pk_fma_f32 v[10:11], v[10:11], v[144:145], v[190:191]
	v_pk_fma_f32 v[2:3], v[2:3], v[144:145], v[194:195]
	v_exp_f32_e32 v12, v12
	v_exp_f32_e32 v4, v4
	v_exp_f32_e32 v13, v13
	v_exp_f32_e32 v5, v5
	v_exp_f32_e32 v14, v14
	v_exp_f32_e32 v6, v6
	v_exp_f32_e32 v15, v15
	v_exp_f32_e32 v7, v7
	v_exp_f32_e32 v8, v8
	v_exp_f32_e32 v0, v0
	v_exp_f32_e32 v9, v9
	v_exp_f32_e32 v1, v1
	v_exp_f32_e32 v10, v10
	v_exp_f32_e32 v2, v2
	v_exp_f32_e32 v11, v11
	v_exp_f32_e32 v3, v3
	s_nop 0
	s_nop 0
	v_pk_add_f32 v[12:13], v[12:13], v[148:149]
	v_pk_add_f32 v[4:5], v[4:5], v[148:149]
	v_pk_add_f32 v[14:15], v[14:15], v[148:149]
	v_pk_add_f32 v[6:7], v[6:7], v[148:149]
	v_pk_add_f32 v[8:9], v[8:9], v[148:149]
	v_pk_add_f32 v[0:1], v[0:1], v[148:149]
	v_pk_add_f32 v[10:11], v[10:11], v[148:149]
	v_pk_add_f32 v[2:3], v[2:3], v[148:149]
	v_rcp_f32_e32 v12, v12
	v_rcp_f32_e32 v4, v4
	v_rcp_f32_e32 v13, v13
	v_rcp_f32_e32 v5, v5
	v_rcp_f32_e32 v14, v14
	v_rcp_f32_e32 v6, v6
	v_rcp_f32_e32 v15, v15
	v_rcp_f32_e32 v7, v7
	v_rcp_f32_e32 v8, v8
	v_rcp_f32_e32 v0, v0
	v_rcp_f32_e32 v9, v9
	v_rcp_f32_e32 v1, v1
	v_rcp_f32_e32 v10, v10
	v_rcp_f32_e32 v2, v2
	v_rcp_f32_e32 v11, v11
	v_rcp_f32_e32 v3, v3
	s_nop 0
	s_nop 0
	v_pk_mul_f32 v[12:13], v[12:13], v[196:197]
	v_pk_mul_f32 v[4:5], v[4:5], v[200:201]
	v_pk_mul_f32 v[14:15], v[14:15], v[198:199]
	v_pk_mul_f32 v[6:7], v[6:7], v[202:203]
	v_pk_mul_f32 v[236:237], v[12:13], v[146:147]
	v_pk_mul_f32 v[240:241], v[4:5], v[146:147]
	v_pk_mul_f32 v[238:239], v[14:15], v[146:147]
	v_pk_mul_f32 v[242:243], v[6:7], v[146:147]
	v_exp_f32_e32 v236, v236
	v_exp_f32_e32 v240, v240
	v_exp_f32_e32 v237, v237
	v_exp_f32_e32 v241, v241
	v_exp_f32_e32 v238, v238
	v_exp_f32_e32 v242, v242
	v_exp_f32_e32 v239, v239
	v_exp_f32_e32 v243, v243
	s_nop 0
	s_nop 0
	v_pk_fma_f32 v[236:237], v[236:237], v[236:237], v[148:149] neg_lo:[1,0,0] neg_hi:[1,0,0]
	v_pk_fma_f32 v[240:241], v[240:241], v[240:241], v[148:149] neg_lo:[1,0,0] neg_hi:[1,0,0]
	v_pk_fma_f32 v[238:239], v[238:239], v[238:239], v[148:149] neg_lo:[1,0,0] neg_hi:[1,0,0]
	v_pk_fma_f32 v[242:243], v[242:243], v[242:243], v[148:149] neg_lo:[1,0,0] neg_hi:[1,0,0]
	v_max_f32_e32 v236, 0, v236
	v_max_f32_e32 v240, 0, v240
	v_max_f32_e32 v237, 0, v237
	v_max_f32_e32 v241, 0, v241
	v_max_f32_e32 v238, 0, v238
	v_max_f32_e32 v242, 0, v242
	v_max_f32_e32 v239, 0, v239
	v_max_f32_e32 v243, 0, v243
	v_sqrt_f32_e32 v236, v236
	v_sqrt_f32_e32 v240, v240
	v_sqrt_f32_e32 v237, v237
	v_sqrt_f32_e32 v241, v241
	v_sqrt_f32_e32 v238, v238
	v_sqrt_f32_e32 v242, v242
	v_sqrt_f32_e32 v239, v239
	v_sqrt_f32_e32 v243, v243
	s_nop 0
	s_nop 0
	v_lshlrev_b32_e32 v244, 16, v232
	v_lshlrev_b32_e32 v248, 16, v234
	v_and_b32_e32 v245, 0xffff0000, v232
	v_and_b32_e32 v249, 0xffff0000, v234
	v_lshlrev_b32_e32 v246, 16, v233
	v_lshlrev_b32_e32 v250, 16, v235
	v_and_b32_e32 v247, 0xffff0000, v233
	v_and_b32_e32 v251, 0xffff0000, v235
	v_pk_mul_f32 v[8:9], v[8:9], v[236:237]
	v_pk_mul_f32 v[0:1], v[0:1], v[240:241]
	v_pk_mul_f32 v[10:11], v[10:11], v[238:239]
	v_pk_mul_f32 v[2:3], v[2:3], v[242:243]
	v_pk_mul_f32 v[8:9], v[8:9], v[244:245]
	v_pk_mul_f32 v[0:1], v[0:1], v[248:249]
	v_pk_mul_f32 v[10:11], v[10:11], v[246:247]
	v_pk_mul_f32 v[2:3], v[2:3], v[250:251]
	v_cvt_pk_bf16_f32 v12, v12, v13
	v_cvt_pk_bf16_f32 v13, v14, v15
	v_cvt_pk_bf16_f32 v14, v4, v5
	v_cvt_pk_bf16_f32 v15, v6, v7
	global_store_dwordx4 v63, v[12:15], s[16:17]
	v_cvt_pk_bf16_f32 v8, v8, v9
	v_cvt_pk_bf16_f32 v9, v10, v11
	v_cvt_pk_bf16_f32 v10, v0, v1
	v_cvt_pk_bf16_f32 v11, v2, v3
	global_store_dwordx4 v63, v[8:11], s[18:19]
	s_and_b64 vcc, exec, s[4:5]
	s_mov_b64 s[4:5], -1
	s_cbranch_vccnz .LBB0_797
	s_and_b64 vcc, exec, s[0:1]
	s_cbranch_vccnz .LBB0_796
	s_barrier
	s_branch .LBB0_796
